# first (layer-0) rownorm row loop software-pipelined too: next row's 8 x loads prefetched with clamped row index, waits reduced to lgkmcnt
# baseline (speedup 1.0000x reference)
; DI unsigned pack2(float lo, float hi) { f32x2 v = {lo, hi}; bf2_t b = __builtin_convertvector(v, bf2_t); return __builtin_bit_cast(unsigned, b); }
; DI float bflo(unsigned u) { return __uint_as_float(u << 16); }
; DI float bfhi(unsigned u) { return __uint_as_float(u & 0xffff0000u); }
; DI float wave_sum(float v) { v += __shfl_xor(v, 32); v += __shfl_xor(v, 16); v += __shfl_xor(v, 8); v += __shfl_xor(v, 4); v += __shfl_xor(v, 2); v += __shfl_xor(v, 1); return v; }
; DI void rownorm_phase(const Params& P, const float* xin, const bf16_t* yin, float* xout, bf16_t* hout, int lg, int gate_idx, const float* w_post,
;                       int lh, int scale_idx, int shift_idx, const float* w_pre, char* smem) {
;     ...
;   for (int row = blockIdx.x * 8 + w; row < S_; row += gridDim.x * 8) {
;     f32x4 xv[8];
; #pragma unroll
;     for (int j = 0; j < 8; ++j) xv[j] = __builtin_nontemporal_load((const f32x4*)(xin + (size_t)row * 2048 + (j * 64 + lane) * 4));
;     if (yin) {
;       f32x4 yv[8]; float ss = 0.f;
; #pragma unroll
;       for (int j = 0; j < 8; ++j) { const u32x2 yb = __builtin_nontemporal_load((const u32x2*)(yin + (size_t)row * 2048 + (j * 64 + lane) * 4)); yv[j] = (f32x4){bflo(yb.x), bfhi(yb.x), bflo(yb.y), bfhi(yb.y)};
;         ss += yv[j].x * yv[j].x + yv[j].y * yv[j].y + yv[j].z * yv[j].z + yv[j].w * yv[j].w; }
;       ss = wave_sum(ss); const float r = rsqrtf(ss * (1.f / 2048.f) + EPS);
; #pragma unroll
;       for (int j = 0; j < 8; ++j) { const f32x4 a = *(const f32x4*)(A1 + (j * 64 + lane) * 4); xv[j] += a * (yv[j] * r); }
;     }
;     if (yin || xout != xin) {
; #pragma unroll
;       for (int j = 0; j < 8; ++j) __builtin_nontemporal_store(xv[j], (f32x4*)(xout + (size_t)row * 2048 + (j * 64 + lane) * 4));
;     }
;     if (hout) {
;       float ss = 0.f;
; #pragma unroll
;       for (int j = 0; j < 8; ++j) ss += xv[j].x * xv[j].x + xv[j].y * xv[j].y + xv[j].z * xv[j].z + xv[j].w * xv[j].w;
;       ss = wave_sum(ss); const float r = rsqrtf(ss * (1.f / 2048.f) + EPS);
; #pragma unroll
;       for (int j = 0; j < 8; ++j) { const f32x4 a = *(const f32x4*)(A2 + (j * 64 + lane) * 4), b = *(const f32x4*)(B2 + (j * 64 + lane) * 4);
;         const f32x4 hv = xv[j] * r * a + b; u32x2 pk = {pack2(hv.x, hv.y), pack2(hv.z, hv.w)};
;         *(u32x2*)(hout + (size_t)row * 2048 + (j * 64 + lane) * 4) = pk; }
.LBB0_107:
	s_or_b64 exec, exec, s[0:1]
	s_add_u32 s60, s40, 0x62e8000
	v_readlane_b32 s0, v254, 0
	v_ashrrev_i32_e32 v1, 6, v0
	s_addc_u32 s61, s41, 0
	s_lshl_b32 s0, s0, 3
	v_writelane_b32 v254, s0, 3
	v_add_u32_e32 v36, s0, v1
	s_movk_i32 s0, 0x4000
	v_cmp_gt_i32_e32 vcc, s0, v36
	v_mbcnt_lo_u32_b32 v207, -1, 0
	s_waitcnt lgkmcnt(0)
	s_barrier
	s_and_saveexec_b64 s[0:1], vcc
	s_cbranch_execz .LBB0_112
	v_mbcnt_hi_u32_b32 v1, -1, v207
	v_and_b32_e32 v5, 64, v1
	s_waitcnt vmcnt(0)
	v_xor_b32_e32 v3, 32, v1
	v_add_u32_e32 v5, 64, v5
	v_cmp_lt_i32_e32 vcc, v3, v5
	v_lshlrev_b32_e32 v0, 2, v0
	v_and_b32_e32 v0, 0xfc, v0
	v_cndmask_b32_e32 v3, v1, v3, vcc
	v_lshlrev_b32_e32 v53, 2, v3
	v_xor_b32_e32 v3, 16, v1
	v_cmp_lt_i32_e32 vcc, v3, v5
	v_mov_b32_e32 v39, 0
	v_lshlrev_b32_e32 v38, 1, v0
	v_cndmask_b32_e32 v3, v1, v3, vcc
	v_lshlrev_b32_e32 v54, 2, v3
	v_xor_b32_e32 v3, 8, v1
	v_cmp_lt_i32_e32 vcc, v3, v5
	v_or_b32_e32 v2, 0x400, v0
	v_or_b32_e32 v4, 0x500, v0
	v_cndmask_b32_e32 v3, v1, v3, vcc
	v_lshlrev_b32_e32 v55, 2, v3
	v_xor_b32_e32 v3, 4, v1
	v_cmp_lt_i32_e32 vcc, v3, v5
	v_or_b32_e32 v6, 0x600, v0
	v_or_b32_e32 v8, 0x700, v0
	v_cndmask_b32_e32 v3, v1, v3, vcc
	v_lshlrev_b32_e32 v56, 2, v3
	v_xor_b32_e32 v3, 2, v1
	v_cmp_lt_i32_e32 vcc, v3, v5
	v_lshlrev_b32_e32 v52, 2, v0
	v_lshl_add_u64 v[40:41], s[60:61], 0, v[38:39]
	v_cndmask_b32_e32 v3, v1, v3, vcc
	v_lshlrev_b32_e32 v57, 2, v3
	v_xor_b32_e32 v3, 1, v1
	v_cmp_lt_i32_e32 vcc, v3, v5
	v_lshlrev_b32_e32 v38, 2, v0
	s_lshl_b32 s6, s42, 3
	v_cndmask_b32_e32 v1, v1, v3, vcc
	v_cmp_ne_u64_e32 vcc, v[34:35], v[32:33]
	v_lshlrev_b32_e32 v58, 2, v1
	s_mov_b64 s[4:5], 0
	v_cndmask_b32_e64 v0, 0, 1, vcc
	v_lshlrev_b32_e32 v42, 2, v2
	v_mov_b32_e32 v43, v39
	v_lshlrev_b32_e32 v44, 2, v4
	v_mov_b32_e32 v45, v39
	v_lshlrev_b32_e32 v46, 2, v6
	v_mov_b32_e32 v47, v39
	v_lshlrev_b32_e32 v48, 2, v8
	v_mov_b32_e32 v49, v39
	v_cmp_ne_u32_e64 s[2:3], 1, v0
	v_mov_b32_e32 v59, 0x358637bd
	s_mov_b32 s7, 0x800000
	s_movk_i32 s8, 0x3fff
	v_mov_b32_e32 v140, v36
	v_ashrrev_i32_e32 v141, 31, v140
	v_lshlrev_b64 v[142:143], 13, v[140:141]
	v_lshl_add_u64 v[142:143], v[32:33], 0, v[142:143]
	v_lshl_add_u64 v[146:147], v[142:143], 0, v[38:39]
	global_load_dwordx4 v[160:163], v[146:147], off nt
	global_load_dwordx4 v[164:167], v[146:147], off offset:1024 nt
	global_load_dwordx4 v[168:171], v[146:147], off offset:2048 nt
	global_load_dwordx4 v[172:175], v[146:147], off offset:3072 nt
	v_lshl_add_u64 v[148:149], v[142:143], 0, v[42:43]
	global_load_dwordx4 v[176:179], v[148:149], off nt
	v_lshl_add_u64 v[148:149], v[142:143], 0, v[44:45]
	global_load_dwordx4 v[180:183], v[148:149], off nt
	v_lshl_add_u64 v[148:149], v[142:143], 0, v[46:47]
	global_load_dwordx4 v[184:187], v[148:149], off nt
	v_lshl_add_u64 v[148:149], v[142:143], 0, v[48:49]
	global_load_dwordx4 v[188:191], v[148:149], off nt
	s_branch .LBB0_110
.LBB0_109:
	s_waitcnt lgkmcnt(0)
	v_mul_f32_e32 v50, v29, v29
	v_mul_f32_e32 v51, v25, v25
	v_fmac_f32_e32 v50, v28, v28
	v_fmac_f32_e32 v51, v24, v24
	v_fmac_f32_e32 v50, v30, v30
	v_fmac_f32_e32 v51, v26, v26
	v_fmac_f32_e32 v50, v31, v31
	v_fmac_f32_e32 v51, v27, v27
	v_add_f32_e32 v50, v50, v51
	v_mul_f32_e32 v51, v21, v21
	v_fmac_f32_e32 v51, v20, v20
	v_fmac_f32_e32 v51, v22, v22
	v_fmac_f32_e32 v51, v23, v23
	v_add_f32_e32 v50, v50, v51
	v_mul_f32_e32 v51, v17, v17
	v_fmac_f32_e32 v51, v16, v16
	v_fmac_f32_e32 v51, v18, v18
	v_fmac_f32_e32 v51, v19, v19
	v_mov_b32_e32 v60, v13
	v_mov_b32_e32 v61, v9
	v_add_f32_e32 v62, v50, v51
	v_mov_b32_e32 v50, v12
	v_mov_b32_e32 v51, v8
	v_pk_mul_f32 v[60:61], v[60:61], v[60:61]
	v_lshlrev_b64 v[72:73], 12, v[36:37]
	v_pk_fma_f32 v[50:51], v[50:51], v[50:51], v[60:61]
	v_mov_b32_e32 v60, v14
	v_mov_b32_e32 v61, v10
	v_pk_fma_f32 v[50:51], v[60:61], v[60:61], v[50:51]
	v_mov_b32_e32 v60, v15
	v_mov_b32_e32 v61, v11
	v_pk_fma_f32 v[50:51], v[60:61], v[60:61], v[50:51]
	v_mov_b32_e32 v60, v5
	v_add_f32_e32 v50, v62, v50
	v_mov_b32_e32 v61, v1
	v_add_f32_e32 v62, v50, v51
	v_mov_b32_e32 v50, v4
	v_mov_b32_e32 v51, v0
	v_pk_mul_f32 v[60:61], v[60:61], v[60:61]
	v_add_u32_e32 v36, s6, v36
	v_pk_fma_f32 v[50:51], v[50:51], v[50:51], v[60:61]
	v_mov_b32_e32 v60, v6
	v_mov_b32_e32 v61, v2
	v_pk_fma_f32 v[50:51], v[60:61], v[60:61], v[50:51]
	v_mov_b32_e32 v60, v7
	v_mov_b32_e32 v61, v3
	v_pk_fma_f32 v[50:51], v[60:61], v[60:61], v[50:51]
	s_nop 0
	v_add_f32_e32 v50, v62, v50
	v_add_f32_e32 v50, v50, v51
	v_mov_b32_e32 v120, v50
	v_mov_b32_e32 v121, v50
	s_nop 1
	v_permlane32_swap_b32_e32 v120, v121
	ds_read_b128 v[60:63], v52 offset:8192
	ds_read_b128 v[64:67], v52 offset:16384
	s_waitcnt lgkmcnt(2)
	v_add_f32_e32 v50, v120, v121
	v_mov_b32_e32 v120, v50
	v_mov_b32_e32 v121, v50
	s_nop 1
	v_permlane16_swap_b32_e32 v120, v121
	s_waitcnt lgkmcnt(0)
	v_add_f32_e32 v50, v120, v121
	s_nop 1
	s_waitcnt lgkmcnt(0)
	v_add_f32_dpp v50, v50, v50 row_ror:8 row_mask:0xf bank_mask:0xf
	s_nop 1
	v_mov_b32_dpp v120, v50 row_ror:4 row_mask:0xf bank_mask:0xa
	v_mov_b32_dpp v120, v50 row_ror:12 row_mask:0xf bank_mask:0x5
	s_waitcnt lgkmcnt(0)
	v_add_f32_e32 v50, v50, v120
	s_nop 1
	s_waitcnt lgkmcnt(0)
	v_add_f32_dpp v50, v50, v50 quad_perm:[2,3,0,1] row_mask:0xf bank_mask:0xf
	s_nop 1
	s_waitcnt lgkmcnt(0)
; DI unsigned pack2(float lo, float hi) { f32x2 v = {lo, hi}; bf2_t b = __builtin_convertvector(v, bf2_t); return __builtin_bit_cast(unsigned, b); }
; DI float bflo(unsigned u) { return __uint_as_float(u << 16); }
; DI float bfhi(unsigned u) { return __uint_as_float(u & 0xffff0000u); }
; DI float wave_sum(float v) { v += __shfl_xor(v, 32); v += __shfl_xor(v, 16); v += __shfl_xor(v, 8); v += __shfl_xor(v, 4); v += __shfl_xor(v, 2); v += __shfl_xor(v, 1); return v; }
; DI void rownorm_phase(const Params& P, const float* xin, const bf16_t* yin, float* xout, bf16_t* hout, int lg, int gate_idx, const float* w_post,
;                       int lh, int scale_idx, int shift_idx, const float* w_pre, char* smem) {
;     ...
;   for (int row = blockIdx.x * 8 + w; row < S_; row += gridDim.x * 8) {
;     f32x4 xv[8];
; #pragma unroll
;     for (int j = 0; j < 8; ++j) xv[j] = __builtin_nontemporal_load((const f32x4*)(xin + (size_t)row * 2048 + (j * 64 + lane) * 4));
;     if (yin) {
;       f32x4 yv[8]; float ss = 0.f;
; #pragma unroll
;       for (int j = 0; j < 8; ++j) { const u32x2 yb = __builtin_nontemporal_load((const u32x2*)(yin + (size_t)row * 2048 + (j * 64 + lane) * 4)); yv[j] = (f32x4){bflo(yb.x), bfhi(yb.x), bflo(yb.y), bfhi(yb.y)};
;         ss += yv[j].x * yv[j].x + yv[j].y * yv[j].y + yv[j].z * yv[j].z + yv[j].w * yv[j].w; }
;       ss = wave_sum(ss); const float r = rsqrtf(ss * (1.f / 2048.f) + EPS);
; #pragma unroll
;       for (int j = 0; j < 8; ++j) { const f32x4 a = *(const f32x4*)(A1 + (j * 64 + lane) * 4); xv[j] += a * (yv[j] * r); }
;     }
;     if (yin || xout != xin) {
; #pragma unroll
;       for (int j = 0; j < 8; ++j) __builtin_nontemporal_store(xv[j], (f32x4*)(xout + (size_t)row * 2048 + (j * 64 + lane) * 4));
;     ...
;     if (hout) {
;       float ss = 0.f;
; #pragma unroll
;       for (int j = 0; j < 8; ++j) ss += xv[j].x * xv[j].x + xv[j].y * xv[j].y + xv[j].z * xv[j].z + xv[j].w * xv[j].w;
;       ss = wave_sum(ss); const float r = rsqrtf(ss * (1.f / 2048.f) + EPS);
; #pragma unroll
;       for (int j = 0; j < 8; ++j) { const f32x4 a = *(const f32x4*)(A2 + (j * 64 + lane) * 4), b = *(const f32x4*)(B2 + (j * 64 + lane) * 4);
;         const f32x4 hv = xv[j] * r * a + b; u32x2 pk = {pack2(hv.x, hv.y), pack2(hv.z, hv.w)};
;         *(u32x2*)(hout + (size_t)row * 2048 + (j * 64 + lane) * 4) = pk; }
	v_add_f32_dpp v50, v50, v50 quad_perm:[1,0,3,2] row_mask:0xf bank_mask:0xf
	v_fmamk_f32 v50, v50, 0x3a000000, v59
	v_mul_f32_e32 v51, 0x4b800000, v50
	v_cmp_gt_f32_e32 vcc, s7, v50
	s_nop 1
	v_cndmask_b32_e32 v50, v50, v51, vcc
	v_rsq_f32_e32 v50, v50
	s_nop 0
	v_mul_f32_e32 v51, 0x45800000, v50
	v_cndmask_b32_e32 v50, v50, v51, vcc
	v_pk_mul_f32 v[74:75], v[28:29], v[50:51] op_sel_hi:[1,0]
	v_pk_mul_f32 v[76:77], v[30:31], v[50:51] op_sel_hi:[1,0]
	ds_read_b128 v[28:31], v52 offset:9216
	ds_read_b128 v[68:71], v52 offset:17408
	v_pk_mul_f32 v[24:25], v[24:25], v[50:51] op_sel_hi:[1,0]
	v_pk_mul_f32 v[26:27], v[26:27], v[50:51] op_sel_hi:[1,0]
	v_pk_fma_f32 v[62:63], v[62:63], v[76:77], v[66:67]
	v_pk_fma_f32 v[60:61], v[60:61], v[74:75], v[64:65]
	s_waitcnt lgkmcnt(0)
	v_pk_fma_f32 v[26:27], v[30:31], v[26:27], v[70:71]
	v_pk_fma_f32 v[24:25], v[28:29], v[24:25], v[68:69]
	v_cvt_pk_bf16_f32 v60, v60, v61
	v_cvt_pk_bf16_f32 v61, v62, v63
	v_lshl_add_u64 v[64:65], v[40:41], 0, v[72:73]
	v_cvt_pk_bf16_f32 v24, v24, v25
	v_cvt_pk_bf16_f32 v25, v26, v27
	global_store_dwordx2 v[64:65], v[60:61], off
	global_store_dwordx2 v[64:65], v[24:25], off offset:512
	ds_read_b128 v[24:27], v52 offset:10240
	ds_read_b128 v[28:31], v52 offset:18432
	v_pk_mul_f32 v[66:67], v[20:21], v[50:51] op_sel_hi:[1,0]
	v_pk_mul_f32 v[68:69], v[22:23], v[50:51] op_sel_hi:[1,0]
	ds_read_b128 v[20:23], v52 offset:11264
	ds_read_b128 v[60:63], v52 offset:19456
	v_pk_mul_f32 v[16:17], v[16:17], v[50:51] op_sel_hi:[1,0]
	v_pk_mul_f32 v[18:19], v[18:19], v[50:51] op_sel_hi:[1,0]
	s_waitcnt lgkmcnt(2)
	v_pk_fma_f32 v[26:27], v[26:27], v[68:69], v[30:31]
	v_pk_fma_f32 v[24:25], v[24:25], v[66:67], v[28:29]
	s_waitcnt lgkmcnt(0)
	v_pk_fma_f32 v[18:19], v[22:23], v[18:19], v[62:63]
	v_pk_fma_f32 v[16:17], v[20:21], v[16:17], v[60:61]
	v_cvt_pk_bf16_f32 v24, v24, v25
	v_cvt_pk_bf16_f32 v25, v26, v27
	v_cvt_pk_bf16_f32 v16, v16, v17
	v_cvt_pk_bf16_f32 v17, v18, v19
	global_store_dwordx2 v[64:65], v[24:25], off offset:1024
	global_store_dwordx2 v[64:65], v[16:17], off offset:1536
	ds_read_b128 v[16:19], v52 offset:12288
	ds_read_b128 v[20:23], v52 offset:20480
	v_pk_mul_f32 v[28:29], v[12:13], v[50:51] op_sel_hi:[1,0]
	v_pk_mul_f32 v[30:31], v[14:15], v[50:51] op_sel_hi:[1,0]
	ds_read_b128 v[12:15], v52 offset:13312
	ds_read_b128 v[24:27], v52 offset:21504
	v_pk_mul_f32 v[8:9], v[8:9], v[50:51] op_sel_hi:[1,0]
	v_pk_mul_f32 v[10:11], v[10:11], v[50:51] op_sel_hi:[1,0]
	s_waitcnt lgkmcnt(2)
	v_pk_fma_f32 v[18:19], v[30:31], v[18:19], v[22:23]
	v_pk_fma_f32 v[16:17], v[28:29], v[16:17], v[20:21]
	s_waitcnt lgkmcnt(0)
	v_pk_fma_f32 v[10:11], v[10:11], v[14:15], v[26:27]
	v_pk_fma_f32 v[8:9], v[8:9], v[12:13], v[24:25]
	v_cvt_pk_bf16_f32 v16, v16, v17
	v_cvt_pk_bf16_f32 v17, v18, v19
	v_cvt_pk_bf16_f32 v8, v8, v9
	v_cvt_pk_bf16_f32 v9, v10, v11
	global_store_dwordx2 v[64:65], v[16:17], off offset:2048
	global_store_dwordx2 v[64:65], v[8:9], off offset:2560
	ds_read_b128 v[8:11], v52 offset:14336
	ds_read_b128 v[12:15], v52 offset:22528
	v_pk_mul_f32 v[20:21], v[4:5], v[50:51] op_sel_hi:[1,0]
	v_pk_mul_f32 v[22:23], v[6:7], v[50:51] op_sel_hi:[1,0]
	ds_read_b128 v[4:7], v52 offset:15360
	ds_read_b128 v[16:19], v52 offset:23552
	v_pk_mul_f32 v[0:1], v[0:1], v[50:51] op_sel_hi:[1,0]
	v_pk_mul_f32 v[2:3], v[2:3], v[50:51] op_sel_hi:[1,0]
	s_waitcnt lgkmcnt(2)
	v_pk_fma_f32 v[10:11], v[22:23], v[10:11], v[14:15]
	v_pk_fma_f32 v[8:9], v[20:21], v[8:9], v[12:13]
	s_waitcnt lgkmcnt(0)
	v_pk_fma_f32 v[2:3], v[2:3], v[6:7], v[18:19]
	v_pk_fma_f32 v[0:1], v[0:1], v[4:5], v[16:17]
	v_cmp_lt_i32_e32 vcc, s8, v36
	v_cvt_pk_bf16_f32 v8, v8, v9
	v_cvt_pk_bf16_f32 v9, v10, v11
	v_cvt_pk_bf16_f32 v0, v0, v1
	v_cvt_pk_bf16_f32 v1, v2, v3
	s_or_b64 s[4:5], vcc, s[4:5]
	global_store_dwordx2 v[64:65], v[8:9], off offset:3072
	global_store_dwordx2 v[64:65], v[0:1], off offset:3584
	s_andn2_b64 exec, exec, s[4:5]
	s_cbranch_execz .LBB0_112
.LBB0_110:
	v_ashrrev_i32_e32 v37, 31, v36
	v_lshlrev_b64 v[50:51], 13, v[36:37]
	s_waitcnt vmcnt(0)
	v_mov_b64_e32 v[28:29], v[160:161]
	v_mov_b64_e32 v[30:31], v[162:163]
	v_mov_b64_e32 v[24:25], v[164:165]
	v_mov_b64_e32 v[26:27], v[166:167]
	v_mov_b64_e32 v[20:21], v[168:169]
	v_mov_b64_e32 v[22:23], v[170:171]
	v_mov_b64_e32 v[16:17], v[172:173]
	v_mov_b64_e32 v[18:19], v[174:175]
	v_mov_b64_e32 v[12:13], v[176:177]
	v_mov_b64_e32 v[14:15], v[178:179]
	v_mov_b64_e32 v[8:9], v[180:181]
	v_mov_b64_e32 v[10:11], v[182:183]
	v_mov_b64_e32 v[4:5], v[184:185]
	v_mov_b64_e32 v[6:7], v[186:187]
	v_mov_b64_e32 v[0:1], v[188:189]
	v_mov_b64_e32 v[2:3], v[190:191]
	v_add_u32_e32 v140, s6, v36
	v_min_i32_e32 v140, 0x3fff, v140
	v_ashrrev_i32_e32 v141, 31, v140
	v_lshlrev_b64 v[142:143], 13, v[140:141]
	v_lshl_add_u64 v[142:143], v[32:33], 0, v[142:143]
	v_lshl_add_u64 v[146:147], v[142:143], 0, v[38:39]
	global_load_dwordx4 v[160:163], v[146:147], off nt
	global_load_dwordx4 v[164:167], v[146:147], off offset:1024 nt
	global_load_dwordx4 v[168:171], v[146:147], off offset:2048 nt
	global_load_dwordx4 v[172:175], v[146:147], off offset:3072 nt
	v_lshl_add_u64 v[148:149], v[142:143], 0, v[42:43]
	global_load_dwordx4 v[176:179], v[148:149], off nt
	v_lshl_add_u64 v[148:149], v[142:143], 0, v[44:45]
	global_load_dwordx4 v[180:183], v[148:149], off nt
	v_lshl_add_u64 v[148:149], v[142:143], 0, v[46:47]
	global_load_dwordx4 v[184:187], v[148:149], off nt
	v_lshl_add_u64 v[148:149], v[142:143], 0, v[48:49]
	global_load_dwordx4 v[188:191], v[148:149], off nt
	s_and_b64 vcc, exec, s[2:3]
	s_cbranch_vccnz .LBB0_109
	v_lshl_add_u64 v[50:51], v[34:35], 0, v[50:51]
	v_lshl_add_u64 v[60:61], v[50:51], 0, v[38:39]
	s_waitcnt lgkmcnt(0)
	global_store_dwordx4 v[60:61], v[28:31], off nt
	global_store_dwordx4 v[60:61], v[24:27], off offset:1024 nt
	global_store_dwordx4 v[60:61], v[20:23], off offset:2048 nt
	global_store_dwordx4 v[60:61], v[16:19], off offset:3072 nt
	v_lshl_add_u64 v[60:61], v[50:51], 0, v[42:43]
	global_store_dwordx4 v[60:61], v[12:15], off nt
	v_lshl_add_u64 v[60:61], v[50:51], 0, v[44:45]
	global_store_dwordx4 v[60:61], v[8:11], off nt
	v_lshl_add_u64 v[60:61], v[50:51], 0, v[46:47]
	v_lshl_add_u64 v[50:51], v[50:51], 0, v[48:49]
	global_store_dwordx4 v[60:61], v[4:7], off nt
	global_store_dwordx4 v[50:51], v[0:3], off nt
	s_branch .LBB0_109
